# S4 rebalance (mem blocks of projection streams moved to FoX streams 96-159) + S3 logits prepass loads batched + S7 stores without nt
# speedup vs baseline: 1.0134x; 1.0084x over previous
.LBB0_560:
	v_ashrrev_i32_e32 v17, 31, v16
	v_lshlrev_b64 v[0:1], 12, v[16:17]
	v_lshl_add_u64 v[4:5], v[14:15], 0, v[0:1]
	s_mov_b64 s[4:5], 0
	v_mov_b32_e32 v0, 0
	v_mov_b32_e32 v1, v9
	v_mov_b32_e32 v2, v9
	v_mov_b32_e32 v3, v9
	v_lshl_add_u32 v20, s1, 4, v28
	v_ashrrev_i32_e32 v21, 31, v20
	v_lshl_add_u64 v[22:23], v[20:21], 2, s[18:19]
	global_load_dwordx4 v[250:253], v[22:23], off
	s_mov_b64 s[4:5], exec
	s_and_b64 exec, exec, s[6:7]
	global_load_dword v17, v[10:11], off
	s_mov_b64 exec, s[4:5]
	v_add_co_u32_e32 v6, vcc, 0x19900000, v4
	s_nop 1
	v_addc_co_u32_e32 v7, vcc, 0, v5, vcc
	v_add_co_u32_e32 v24, vcc, 0x9600000, v12
	s_nop 1
	v_addc_co_u32_e32 v25, vcc, 0, v13, vcc
	global_load_dwordx4 v[98:101], v[6:7], off
	global_load_dwordx4 v[102:105], v[6:7], off offset:64
	global_load_dwordx4 v[106:109], v[6:7], off offset:128
	global_load_dwordx4 v[110:113], v[6:7], off offset:192
	global_load_dwordx4 v[114:117], v[6:7], off offset:256
	global_load_dwordx4 v[118:121], v[6:7], off offset:320
	global_load_dwordx4 v[122:125], v[6:7], off offset:384
	global_load_dwordx4 v[126:129], v[6:7], off offset:448
	global_load_dwordx4 v[130:133], v[6:7], off offset:512
	global_load_dwordx4 v[134:137], v[6:7], off offset:576
	global_load_dwordx4 v[138:141], v[6:7], off offset:640
	global_load_dwordx4 v[142:145], v[6:7], off offset:704
	global_load_dwordx4 v[146:149], v[6:7], off offset:768
	global_load_dwordx4 v[150:153], v[6:7], off offset:832
	global_load_dwordx4 v[154:157], v[6:7], off offset:896
	global_load_dwordx4 v[158:161], v[6:7], off offset:960
	global_load_dwordx4 v[162:165], v[24:25], off
	global_load_dwordx4 v[166:169], v[24:25], off offset:64
	global_load_dwordx4 v[170:173], v[24:25], off offset:128
	global_load_dwordx4 v[174:177], v[24:25], off offset:192
	global_load_dwordx4 v[178:181], v[24:25], off offset:256
	global_load_dwordx4 v[182:185], v[24:25], off offset:320
	global_load_dwordx4 v[186:189], v[24:25], off offset:384
	global_load_dwordx4 v[190:193], v[24:25], off offset:448
	global_load_dwordx4 v[194:197], v[24:25], off offset:512
	global_load_dwordx4 v[198:201], v[24:25], off offset:576
	global_load_dwordx4 v[202:205], v[24:25], off offset:640
	global_load_dwordx4 v[206:209], v[24:25], off offset:704
	global_load_dwordx4 v[210:213], v[24:25], off offset:768
	global_load_dwordx4 v[214:217], v[24:25], off offset:832
	global_load_dwordx4 v[218:221], v[24:25], off offset:896
	global_load_dwordx4 v[222:225], v[24:25], off offset:960
	global_load_dwordx4 v[34:37], v[6:7], off offset:1024
	global_load_dwordx4 v[38:41], v[6:7], off offset:1088
	global_load_dwordx4 v[42:45], v[6:7], off offset:1152
	global_load_dwordx4 v[46:49], v[6:7], off offset:1216
	global_load_dwordx4 v[50:53], v[6:7], off offset:1280
	global_load_dwordx4 v[54:57], v[6:7], off offset:1344
	global_load_dwordx4 v[58:61], v[6:7], off offset:1408
	global_load_dwordx4 v[62:65], v[6:7], off offset:1472
	global_load_dwordx4 v[66:69], v[6:7], off offset:1536
	global_load_dwordx4 v[70:73], v[6:7], off offset:1600
	global_load_dwordx4 v[74:77], v[6:7], off offset:1664
	global_load_dwordx4 v[78:81], v[24:25], off offset:1024
	global_load_dwordx4 v[82:85], v[24:25], off offset:1088
	global_load_dwordx4 v[86:89], v[24:25], off offset:1152
	global_load_dwordx4 v[90:93], v[24:25], off offset:1216
	global_load_dwordx4 v[94:97], v[24:25], off offset:1280
	global_load_dwordx4 v[226:229], v[24:25], off offset:1344
	global_load_dwordx4 v[230:233], v[24:25], off offset:1408
	global_load_dwordx4 v[234:237], v[24:25], off offset:1472
	global_load_dwordx4 v[238:241], v[24:25], off offset:1536
	global_load_dwordx4 v[242:245], v[24:25], off offset:1600
	global_load_dwordx4 v[246:249], v[24:25], off offset:1664
	s_waitcnt vmcnt(22)
	v_mfma_f32_16x16x32_bf16 v[0:3], v[98:101], v[162:165], v[0:3]
	v_mfma_f32_16x16x32_bf16 v[0:3], v[102:105], v[166:169], v[0:3]
	v_mfma_f32_16x16x32_bf16 v[0:3], v[106:109], v[170:173], v[0:3]
	v_mfma_f32_16x16x32_bf16 v[0:3], v[110:113], v[174:177], v[0:3]
	v_mfma_f32_16x16x32_bf16 v[0:3], v[114:117], v[178:181], v[0:3]
	v_mfma_f32_16x16x32_bf16 v[0:3], v[118:121], v[182:185], v[0:3]
	v_mfma_f32_16x16x32_bf16 v[0:3], v[122:125], v[186:189], v[0:3]
	v_mfma_f32_16x16x32_bf16 v[0:3], v[126:129], v[190:193], v[0:3]
	v_mfma_f32_16x16x32_bf16 v[0:3], v[130:133], v[194:197], v[0:3]
	v_mfma_f32_16x16x32_bf16 v[0:3], v[134:137], v[198:201], v[0:3]
	v_mfma_f32_16x16x32_bf16 v[0:3], v[138:141], v[202:205], v[0:3]
	v_mfma_f32_16x16x32_bf16 v[0:3], v[142:145], v[206:209], v[0:3]
	v_mfma_f32_16x16x32_bf16 v[0:3], v[146:149], v[210:213], v[0:3]
	v_mfma_f32_16x16x32_bf16 v[0:3], v[150:153], v[214:217], v[0:3]
	v_mfma_f32_16x16x32_bf16 v[0:3], v[154:157], v[218:221], v[0:3]
	v_mfma_f32_16x16x32_bf16 v[0:3], v[158:161], v[222:225], v[0:3]
	global_load_dwordx4 v[98:101], v[6:7], off offset:1728
	global_load_dwordx4 v[102:105], v[6:7], off offset:1792
	global_load_dwordx4 v[106:109], v[6:7], off offset:1856
	global_load_dwordx4 v[110:113], v[6:7], off offset:1920
	global_load_dwordx4 v[114:117], v[6:7], off offset:1984
	global_load_dwordx4 v[162:165], v[24:25], off offset:1728
	global_load_dwordx4 v[166:169], v[24:25], off offset:1792
	global_load_dwordx4 v[170:173], v[24:25], off offset:1856
	global_load_dwordx4 v[174:177], v[24:25], off offset:1920
	global_load_dwordx4 v[178:181], v[24:25], off offset:1984
	s_waitcnt vmcnt(10)
	v_mfma_f32_16x16x32_bf16 v[0:3], v[34:37], v[78:81], v[0:3]
	v_mfma_f32_16x16x32_bf16 v[0:3], v[38:41], v[82:85], v[0:3]
	v_mfma_f32_16x16x32_bf16 v[0:3], v[42:45], v[86:89], v[0:3]
	v_mfma_f32_16x16x32_bf16 v[0:3], v[46:49], v[90:93], v[0:3]
	v_mfma_f32_16x16x32_bf16 v[0:3], v[50:53], v[94:97], v[0:3]
	v_mfma_f32_16x16x32_bf16 v[0:3], v[54:57], v[226:229], v[0:3]
	v_mfma_f32_16x16x32_bf16 v[0:3], v[58:61], v[230:233], v[0:3]
	v_mfma_f32_16x16x32_bf16 v[0:3], v[62:65], v[234:237], v[0:3]
	v_mfma_f32_16x16x32_bf16 v[0:3], v[66:69], v[238:241], v[0:3]
	v_mfma_f32_16x16x32_bf16 v[0:3], v[70:73], v[242:245], v[0:3]
	v_mfma_f32_16x16x32_bf16 v[0:3], v[74:77], v[246:249], v[0:3]
	s_waitcnt vmcnt(0)
	v_mfma_f32_16x16x32_bf16 v[0:3], v[98:101], v[162:165], v[0:3]
	v_mfma_f32_16x16x32_bf16 v[0:3], v[102:105], v[166:169], v[0:3]
	v_mfma_f32_16x16x32_bf16 v[0:3], v[106:109], v[170:173], v[0:3]
	v_mfma_f32_16x16x32_bf16 v[0:3], v[110:113], v[174:177], v[0:3]
	v_mfma_f32_16x16x32_bf16 v[0:3], v[114:117], v[178:181], v[0:3]
	s_nop 1
	s_and_b64 vcc, exec, s[50:51]
	s_cbranch_vccz .LBB0_564
	s_nop 4
	ds_write_b128 v27, v[0:3]
.LBB0_564:
	s_and_b64 vcc, exec, s[8:9]
	s_waitcnt lgkmcnt(0)
	s_barrier
	s_cbranch_vccnz .LBB0_559
	s_and_saveexec_b64 s[16:17], s[6:7]
	s_cbranch_execz .LBB0_558
	v_lshl_add_u32 v20, s1, 4, v28
	v_ashrrev_i32_e32 v21, 31, v20
	v_lshl_add_u64 v[22:23], v[20:21], 2, s[18:19]
	v_mov_b32_e32 v4, v250
	s_waitcnt vmcnt(0) lgkmcnt(0)
	v_fmamk_f32 v4, v4, 0x3a000000, v29
	v_mul_f32_e32 v5, 0x4f800000, v4
	v_cmp_gt_f32_e32 vcc, s14, v4
	s_nop 1
	v_cndmask_b32_e32 v4, v4, v5, vcc
	v_sqrt_f32_e32 v5, v4
	s_nop 0
	v_add_u32_e32 v6, -1, v5
	v_add_u32_e32 v7, 1, v5
	v_fma_f32 v8, -v6, v5, v4
	v_fma_f32 v19, -v7, v5, v4
	v_cmp_ge_f32_e64 s[10:11], 0, v8
	s_nop 1
	v_cndmask_b32_e64 v5, v5, v6, s[10:11]
	v_cmp_lt_f32_e64 s[10:11], 0, v19
	s_nop 1
	v_cndmask_b32_e64 v5, v5, v7, s[10:11]
	v_mul_f32_e32 v6, 0x37800000, v5
	v_cndmask_b32_e32 v5, v5, v6, vcc
	v_cmp_class_f32_e32 vcc, v4, v30
	s_nop 1
	v_cndmask_b32_e32 v8, v5, v4, vcc
	v_div_scale_f32 v19, s[4:5], v8, v8, 1.0
	v_rcp_f32_e32 v21, v19
	v_div_scale_f32 v24, vcc, 1.0, v8, 1.0
	ds_read_b128 v[4:7], v27
	v_fma_f32 v25, -v19, v21, 1.0
	v_fmac_f32_e32 v21, v25, v21
	v_mul_f32_e32 v25, v24, v21
	v_fma_f32 v33, -v19, v25, v24
	v_fmac_f32_e32 v25, v33, v21
	v_fma_f32 v19, -v19, v25, v24
	v_div_fmas_f32 v19, v19, v21, v25
	v_div_fixup_f32 v8, v19, v8, 1.0
	s_waitcnt lgkmcnt(0)
	v_add_f32_e32 v0, v0, v4
	v_fma_f32 v0, v0, v8, v17
	v_cmp_ngt_f32_e32 vcc, 0, v0
	s_and_saveexec_b64 s[4:5], vcc
	s_xor_b64 s[4:5], exec, s[4:5]
	s_cbranch_execz .LBB0_568
	v_mul_f32_e32 v4, 0xbfb8aa3b, v0
	v_rndne_f32_e32 v8, v4
	v_sub_f32_e32 v19, v4, v8
	v_fma_f32 v4, v0, s15, -v4
	v_fmac_f32_e32 v4, 0xb2a5705f, v0
	v_add_f32_e32 v4, v19, v4
	v_cvt_i32_f32_e32 v8, v8
	v_exp_f32_e32 v4, v4
	v_cmp_nlt_f32_e32 vcc, s20, v0
	v_ldexp_f32 v4, v4, v8
	s_nop 0
	v_cndmask_b32_e32 v4, 0, v4, vcc
	v_cmp_ngt_f32_e32 vcc, s21, v0
	s_nop 1
	v_cndmask_b32_e32 v0, v32, v4, vcc
	v_add_f32_e32 v4, 1.0, v0
	v_add_f32_e32 v8, -1.0, v4
	v_sub_f32_e32 v19, v8, v4
	v_add_f32_e32 v19, 1.0, v19
	v_sub_f32_e32 v8, v0, v8
	v_add_f32_e32 v8, v8, v19
	v_frexp_mant_f32_e32 v19, v4
	v_cvt_f64_f32_e32 v[24:25], v4
	v_frexp_exp_i32_f64_e32 v21, v[24:25]
	v_cmp_gt_f32_e32 vcc, s23, v19
	s_nop 1
	v_subbrev_co_u32_e32 v21, vcc, 0, v21, vcc
	v_sub_u32_e32 v19, 0, v21
	v_ldexp_f32 v4, v4, v19
	v_ldexp_f32 v8, v8, v19
	v_add_f32_e32 v19, -1.0, v4
	v_add_f32_e32 v25, 1.0, v4
	v_add_f32_e32 v24, 1.0, v19
	v_add_f32_e32 v33, -1.0, v25
	v_sub_f32_e32 v24, v4, v24
	v_sub_f32_e32 v4, v4, v33
	v_add_f32_e32 v4, v8, v4
	v_add_f32_e32 v24, v8, v24
	v_add_f32_e32 v8, v25, v4
	v_rcp_f32_e32 v33, v8
	v_sub_f32_e32 v25, v25, v8
	v_add_f32_e32 v4, v4, v25
	v_add_f32_e32 v25, v19, v24
	v_mul_f32_e32 v40, v25, v33
	v_mul_f32_e32 v34, v8, v40
	v_fma_f32 v36, v40, v8, -v34
	v_sub_f32_e32 v19, v19, v25
	v_fmac_f32_e32 v36, v40, v4
	v_add_f32_e32 v19, v24, v19
	v_add_f32_e32 v24, v34, v36
	v_sub_f32_e32 v35, v25, v24
	v_pk_add_f32 v[38:39], v[24:25], v[34:35] neg_lo:[0,1] neg_hi:[0,1]
	v_mov_b32_e32 v37, v24
	v_pk_add_f32 v[24:25], v[38:39], v[36:37] neg_lo:[0,1] neg_hi:[0,1]
	v_cmp_neq_f32_e32 vcc, s22, v0
	v_add_f32_e32 v19, v19, v25
	v_add_f32_e32 v19, v24, v19
	v_add_f32_e32 v25, v35, v19
	v_mul_f32_e32 v41, v33, v25
	v_mul_f32_e32 v34, v8, v41
	v_fma_f32 v36, v41, v8, -v34
	v_fmac_f32_e32 v36, v41, v4
	v_add_f32_e32 v24, v34, v36
	v_sub_f32_e32 v4, v35, v25
	v_sub_f32_e32 v35, v25, v24
	v_pk_add_f32 v[38:39], v[24:25], v[34:35] neg_lo:[0,1] neg_hi:[0,1]
	v_mov_b32_e32 v37, v24
	v_add_f32_e32 v4, v19, v4
	v_pk_add_f32 v[24:25], v[38:39], v[36:37] neg_lo:[0,1] neg_hi:[0,1]
	v_add_f32_e32 v8, v40, v41
	v_add_f32_e32 v4, v4, v25
	v_add_f32_e32 v4, v24, v4
	v_add_f32_e32 v4, v35, v4
	v_sub_f32_e32 v19, v8, v40
	v_mul_f32_e32 v4, v33, v4
	v_sub_f32_e32 v19, v41, v19
	v_add_f32_e32 v4, v19, v4
	v_add_f32_e32 v25, v8, v4
	v_cvt_f32_i32_e32 v24, v21
	v_mul_f32_e32 v33, v25, v25
	v_fmamk_f32 v19, v33, 0x3e9b6dac, v31
	v_fmaak_f32 v19, v33, v19, 0x3f2aaada
	v_sub_f32_e32 v8, v25, v8
	v_ldexp_f32 v35, v25, 1
	v_mul_f32_e32 v25, v25, v33
	v_pk_mul_f32 v[36:37], v[24:25], v[18:19]
	v_sub_f32_e32 v4, v4, v8
	v_fma_f32 v34, v24, s24, -v36
	v_fmac_f32_e32 v34, 0xb102e308, v24
	v_pk_add_f32 v[24:25], v[36:37], v[34:35]
	v_ldexp_f32 v4, v4, 1
	v_sub_f32_e32 v8, v25, v35
	v_sub_f32_e32 v8, v37, v8
	v_add_f32_e32 v39, v4, v8
	v_mov_b32_e32 v38, v36
	v_pk_add_f32 v[36:37], v[24:25], v[36:37] neg_lo:[0,1] neg_hi:[0,1]
	v_pk_add_f32 v[40:41], v[24:25], v[38:39]
	v_mov_b32_e32 v35, v24
	v_mov_b32_e32 v37, v41
	v_pk_add_f32 v[42:43], v[34:35], v[36:37] neg_lo:[0,1] neg_hi:[0,1]
	v_pk_add_f32 v[34:35], v[34:35], v[36:37]
	v_mov_b32_e32 v38, v39
	v_pk_add_f32 v[36:37], v[34:35], v[24:25] op_sel:[1,0] op_sel_hi:[0,1] neg_lo:[0,1] neg_hi:[0,1]
	v_pk_add_f32 v[44:45], v[40:41], v[36:37] op_sel_hi:[1,0] neg_lo:[0,1] neg_hi:[0,1]
	v_mov_b32_e32 v40, v41
	v_mov_b32_e32 v41, v35
	v_pk_mov_b32 v[36:37], v[24:25], v[36:37] op_sel:[1,0]
	v_mov_b32_e32 v39, v24
	v_pk_add_f32 v[36:37], v[40:41], v[36:37] neg_lo:[0,1] neg_hi:[0,1]
	v_mov_b32_e32 v44, v42
	v_pk_add_f32 v[24:25], v[38:39], v[36:37] neg_lo:[0,1] neg_hi:[0,1]
	v_mov_b32_e32 v43, v35
	v_pk_add_f32 v[36:37], v[44:45], v[24:25]
	s_nop 0
	v_pk_add_f32 v[38:39], v[36:37], v[36:37] op_sel:[0,1] op_sel_hi:[1,0]
	s_nop 0
	v_pk_add_f32 v[34:35], v[34:35], v[38:39] op_sel:[1,0] op_sel_hi:[0,1]
	v_mov_b32_e32 v37, v34
	v_pk_add_f32 v[40:41], v[36:37], v[42:43] neg_lo:[0,1] neg_hi:[0,1]
	v_mov_b32_e32 v25, v38
	v_sub_f32_e32 v4, v36, v40
	v_pk_add_f32 v[24:25], v[24:25], v[40:41] neg_lo:[0,1] neg_hi:[0,1]
	v_sub_f32_e32 v4, v42, v4
	v_add_f32_e32 v4, v24, v4
	v_add_f32_e32 v4, v4, v25
	v_add_f32_e32 v4, v34, v4
	v_cndmask_b32_e32 v4, v32, v4, vcc
	v_cmp_lt_f32_e64 vcc, |v0|, s25
	s_nop 1
	v_cndmask_b32_e32 v0, v4, v0, vcc
	v_xor_b32_e32 v4, 0x80000000, v0

.LBB0_570:
	s_or_b64 exec, exec, s[4:5]
	v_ashrrev_i32_e32 v0, 12, v20
	v_mad_i32_i24 v24, v0, 6, v26
	v_ashrrev_i32_e32 v25, 31, v24
	v_lshlrev_b64 v[24:25], 14, v[24:25]
	v_and_b32_e32 v0, 0xffc, v20
	v_lshl_add_u64 v[24:25], s[12:13], 0, v[24:25]
	v_lshlrev_b32_e32 v8, 2, v0
	v_lshl_add_u64 v[34:35], v[24:25], 0, v[8:9]
	flat_store_dword v[34:35], v4
	v_mov_b32_e32 v0, v251
	v_add_f32_e32 v1, v1, v5
	v_fmamk_f32 v0, v0, 0x3a000000, v29
	v_mul_f32_e32 v4, 0x4f800000, v0
	v_cmp_gt_f32_e32 vcc, s14, v0
	s_nop 1
	v_cndmask_b32_e32 v0, v0, v4, vcc
	v_sqrt_f32_e32 v4, v0
	s_nop 0
	v_add_u32_e32 v8, -1, v4
	v_add_u32_e32 v19, 1, v4
	v_fma_f32 v21, -v8, v4, v0
	v_fma_f32 v33, -v19, v4, v0
	v_cmp_ge_f32_e64 s[10:11], 0, v21
	s_nop 1
	v_cndmask_b32_e64 v4, v4, v8, s[10:11]
	v_cmp_lt_f32_e64 s[10:11], 0, v33
	s_nop 1
	v_cndmask_b32_e64 v4, v4, v19, s[10:11]
	v_mul_f32_e32 v8, 0x37800000, v4
	v_cndmask_b32_e32 v4, v4, v8, vcc
	v_cmp_class_f32_e32 vcc, v0, v30
	s_nop 1
	v_cndmask_b32_e32 v0, v4, v0, vcc
	v_div_scale_f32 v4, s[4:5], v0, v0, 1.0
	v_rcp_f32_e32 v8, v4
	v_div_scale_f32 v19, vcc, 1.0, v0, 1.0
	v_fma_f32 v21, -v4, v8, 1.0
	v_fmac_f32_e32 v8, v21, v8
	v_mul_f32_e32 v21, v19, v8
	v_fma_f32 v33, -v4, v21, v19
	v_fmac_f32_e32 v21, v33, v8
	v_fma_f32 v4, -v4, v21, v19
	v_div_fmas_f32 v4, v4, v8, v21
	v_div_fixup_f32 v0, v4, v0, 1.0
	v_fma_f32 v0, v1, v0, v17
	v_cmp_ngt_f32_e32 vcc, 0, v0
	s_and_saveexec_b64 s[4:5], vcc
	s_xor_b64 s[4:5], exec, s[4:5]
	s_cbranch_execz .LBB0_572
	v_mul_f32_e32 v1, 0xbfb8aa3b, v0
	v_rndne_f32_e32 v4, v1
	v_sub_f32_e32 v5, v1, v4
	v_fma_f32 v1, v0, s15, -v1
	v_fmac_f32_e32 v1, 0xb2a5705f, v0
	v_add_f32_e32 v1, v5, v1
	v_cvt_i32_f32_e32 v4, v4
	v_exp_f32_e32 v1, v1
	v_cmp_nlt_f32_e32 vcc, s20, v0
	v_ldexp_f32 v1, v1, v4
	s_nop 0
	v_cndmask_b32_e32 v1, 0, v1, vcc
	v_cmp_ngt_f32_e32 vcc, s21, v0
	s_nop 1
	v_cndmask_b32_e32 v8, v32, v1, vcc
	v_add_f32_e32 v4, 1.0, v8
	v_add_f32_e32 v0, -1.0, v4
	v_sub_f32_e32 v1, v0, v4
	v_add_f32_e32 v1, 1.0, v1
	v_sub_f32_e32 v0, v8, v0
	v_add_f32_e32 v5, v0, v1
	v_frexp_mant_f32_e32 v19, v4
	v_cvt_f64_f32_e32 v[0:1], v4
	v_frexp_exp_i32_f64_e32 v0, v[0:1]
	v_cmp_gt_f32_e32 vcc, s23, v19
	s_nop 1
	v_subbrev_co_u32_e32 v21, vcc, 0, v0, vcc
	v_sub_u32_e32 v0, 0, v21
	v_ldexp_f32 v1, v4, v0
	v_add_f32_e32 v4, -1.0, v1
	v_add_f32_e32 v19, 1.0, v1
	v_ldexp_f32 v0, v5, v0
	v_add_f32_e32 v5, 1.0, v4
	v_add_f32_e32 v33, -1.0, v19
	v_sub_f32_e32 v5, v1, v5
	v_sub_f32_e32 v1, v1, v33
	v_add_f32_e32 v5, v0, v5
	v_add_f32_e32 v0, v0, v1
	v_add_f32_e32 v33, v19, v0
	v_rcp_f32_e32 v38, v33
	v_sub_f32_e32 v1, v19, v33
	v_add_f32_e32 v19, v0, v1
	v_add_f32_e32 v1, v4, v5
	v_mul_f32_e32 v40, v1, v38
	v_sub_f32_e32 v0, v4, v1
	v_mul_f32_e32 v4, v33, v40
	v_fma_f32 v34, v40, v33, -v4
	v_fmac_f32_e32 v34, v40, v19
	v_add_f32_e32 v39, v5, v0
	v_add_f32_e32 v0, v4, v34
	v_sub_f32_e32 v5, v1, v0
	v_pk_add_f32 v[36:37], v[0:1], v[4:5] neg_lo:[0,1] neg_hi:[0,1]
	v_mov_b32_e32 v35, v0
	v_pk_add_f32 v[0:1], v[36:37], v[34:35] neg_lo:[0,1] neg_hi:[0,1]
	v_cmp_neq_f32_e32 vcc, s22, v8
	v_add_f32_e32 v1, v39, v1
	v_add_f32_e32 v0, v0, v1
	v_add_f32_e32 v1, v5, v0
	v_mul_f32_e32 v39, v38, v1
	v_mul_f32_e32 v4, v33, v39
	v_fma_f32 v34, v39, v33, -v4
	v_fmac_f32_e32 v34, v39, v19
	v_sub_f32_e32 v5, v5, v1
	v_add_f32_e32 v19, v0, v5
	v_add_f32_e32 v0, v4, v34
	v_sub_f32_e32 v5, v1, v0
	v_pk_add_f32 v[36:37], v[0:1], v[4:5] neg_lo:[0,1] neg_hi:[0,1]
	v_mov_b32_e32 v35, v0
	v_pk_add_f32 v[0:1], v[36:37], v[34:35] neg_lo:[0,1] neg_hi:[0,1]
	s_nop 0
	v_add_f32_e32 v1, v19, v1
	v_add_f32_e32 v0, v0, v1
	v_add_f32_e32 v1, v40, v39
	v_add_f32_e32 v0, v5, v0
	v_sub_f32_e32 v4, v1, v40
	v_mul_f32_e32 v0, v38, v0
	v_sub_f32_e32 v4, v39, v4
	v_add_f32_e32 v4, v4, v0
	v_add_f32_e32 v33, v1, v4
	v_mul_f32_e32 v34, v33, v33
	v_fmamk_f32 v0, v34, 0x3e9b6dac, v31
	v_fmaak_f32 v19, v34, v0, 0x3f2aaada
	v_cvt_f32_i32_e32 v0, v21
	v_sub_f32_e32 v1, v33, v1
	v_sub_f32_e32 v1, v4, v1
	v_ldexp_f32 v21, v1, 1
	v_mul_f32_e32 v1, v33, v34
	v_pk_mul_f32 v[34:35], v[0:1], v[18:19]
	v_ldexp_f32 v5, v33, 1
	v_fma_f32 v4, v0, s24, -v34
	v_fmac_f32_e32 v4, 0xb102e308, v0
	v_pk_add_f32 v[0:1], v[34:35], v[4:5]
	v_mov_b32_e32 v36, v34
	v_sub_f32_e32 v5, v1, v5
	v_sub_f32_e32 v5, v35, v5
	v_add_f32_e32 v37, v21, v5
	v_pk_add_f32 v[34:35], v[0:1], v[34:35] neg_lo:[0,1] neg_hi:[0,1]
	v_pk_add_f32 v[38:39], v[0:1], v[36:37]
	v_mov_b32_e32 v5, v0
	v_mov_b32_e32 v35, v39
	v_pk_add_f32 v[40:41], v[4:5], v[34:35] neg_lo:[0,1] neg_hi:[0,1]
	v_pk_add_f32 v[4:5], v[4:5], v[34:35]
	v_mov_b32_e32 v36, v37
	v_pk_add_f32 v[34:35], v[4:5], v[0:1] op_sel:[1,0] op_sel_hi:[0,1] neg_lo:[0,1] neg_hi:[0,1]
	v_pk_add_f32 v[42:43], v[38:39], v[34:35] op_sel_hi:[1,0] neg_lo:[0,1] neg_hi:[0,1]
	v_mov_b32_e32 v38, v39
	v_mov_b32_e32 v39, v5
	v_pk_mov_b32 v[34:35], v[0:1], v[34:35] op_sel:[1,0]
	v_mov_b32_e32 v37, v0
	v_pk_add_f32 v[34:35], v[38:39], v[34:35] neg_lo:[0,1] neg_hi:[0,1]
	v_mov_b32_e32 v42, v40
	v_pk_add_f32 v[0:1], v[36:37], v[34:35] neg_lo:[0,1] neg_hi:[0,1]
	v_mov_b32_e32 v41, v5
	v_pk_add_f32 v[34:35], v[42:43], v[0:1]
	s_nop 0
	v_pk_add_f32 v[36:37], v[34:35], v[34:35] op_sel:[0,1] op_sel_hi:[1,0]
	s_nop 0
	v_pk_add_f32 v[4:5], v[4:5], v[36:37] op_sel:[1,0] op_sel_hi:[0,1]
	v_mov_b32_e32 v35, v4
	v_pk_add_f32 v[38:39], v[34:35], v[40:41] neg_lo:[0,1] neg_hi:[0,1]
	v_mov_b32_e32 v1, v36
	v_sub_f32_e32 v5, v34, v38
	v_pk_add_f32 v[0:1], v[0:1], v[38:39] neg_lo:[0,1] neg_hi:[0,1]
	v_sub_f32_e32 v5, v40, v5
	v_add_f32_e32 v0, v0, v5
	v_add_f32_e32 v0, v0, v1
	v_add_f32_e32 v0, v4, v0
	v_cndmask_b32_e32 v0, v32, v0, vcc
	v_cmp_lt_f32_e64 vcc, |v8|, s25
	s_nop 1
	v_cndmask_b32_e32 v0, v0, v8, vcc
	v_xor_b32_e32 v1, 0x80000000, v0

.LBB0_574:
	s_or_b64 exec, exec, s[4:5]
	v_bitop3_b32 v0, v20, s29, 1 bitop3:0xc8
	v_lshlrev_b32_e32 v8, 2, v0
	v_lshl_add_u64 v[4:5], v[24:25], 0, v[8:9]
	flat_store_dword v[4:5], v1
	v_mov_b32_e32 v0, v252
	v_fmamk_f32 v0, v0, 0x3a000000, v29
	v_mul_f32_e32 v1, 0x4f800000, v0
	v_cmp_gt_f32_e32 vcc, s14, v0
	s_nop 1
	v_cndmask_b32_e32 v0, v0, v1, vcc
	v_sqrt_f32_e32 v1, v0
	s_nop 0
	v_add_u32_e32 v4, -1, v1
	v_add_u32_e32 v5, 1, v1
	v_fma_f32 v8, -v4, v1, v0
	v_fma_f32 v19, -v5, v1, v0
	v_cmp_ge_f32_e64 s[10:11], 0, v8
	s_nop 1
	v_cndmask_b32_e64 v1, v1, v4, s[10:11]
	v_cmp_lt_f32_e64 s[10:11], 0, v19
	s_nop 1
	v_cndmask_b32_e64 v1, v1, v5, s[10:11]
	v_mul_f32_e32 v4, 0x37800000, v1
	v_cndmask_b32_e32 v1, v1, v4, vcc
	v_cmp_class_f32_e32 vcc, v0, v30
	s_nop 1
	v_cndmask_b32_e32 v0, v1, v0, vcc
	v_div_scale_f32 v1, s[4:5], v0, v0, 1.0
	v_rcp_f32_e32 v4, v1
	v_div_scale_f32 v5, vcc, 1.0, v0, 1.0
	v_fma_f32 v8, -v1, v4, 1.0
	v_fmac_f32_e32 v4, v8, v4
	v_mul_f32_e32 v8, v5, v4
	v_fma_f32 v19, -v1, v8, v5
	v_fmac_f32_e32 v8, v19, v4
	v_fma_f32 v1, -v1, v8, v5
	v_div_fmas_f32 v1, v1, v4, v8
	v_div_fixup_f32 v0, v1, v0, 1.0
	v_add_f32_e32 v1, v2, v6
	v_fma_f32 v0, v1, v0, v17
	v_cmp_ngt_f32_e32 vcc, 0, v0
	s_and_saveexec_b64 s[4:5], vcc
	s_xor_b64 s[4:5], exec, s[4:5]
	s_cbranch_execz .LBB0_576
	v_mul_f32_e32 v1, 0xbfb8aa3b, v0
	v_rndne_f32_e32 v2, v1
	v_sub_f32_e32 v4, v1, v2
	v_fma_f32 v1, v0, s15, -v1
	v_fmac_f32_e32 v1, 0xb2a5705f, v0
	v_add_f32_e32 v1, v4, v1
	v_cvt_i32_f32_e32 v2, v2
	v_exp_f32_e32 v1, v1
	v_cmp_nlt_f32_e32 vcc, s20, v0
	v_ldexp_f32 v1, v1, v2
	s_nop 0
	v_cndmask_b32_e32 v1, 0, v1, vcc
	v_cmp_ngt_f32_e32 vcc, s21, v0
	s_nop 1
	v_cndmask_b32_e32 v2, v32, v1, vcc
	v_add_f32_e32 v4, 1.0, v2
	v_add_f32_e32 v0, -1.0, v4
	v_sub_f32_e32 v1, v0, v4
	v_add_f32_e32 v1, 1.0, v1
	v_sub_f32_e32 v0, v2, v0
	v_add_f32_e32 v5, v0, v1
	v_frexp_mant_f32_e32 v6, v4
	v_cvt_f64_f32_e32 v[0:1], v4
	v_frexp_exp_i32_f64_e32 v0, v[0:1]
	v_cmp_gt_f32_e32 vcc, s23, v6
	s_nop 1
	v_subbrev_co_u32_e32 v6, vcc, 0, v0, vcc
	v_sub_u32_e32 v0, 0, v6
	v_ldexp_f32 v1, v4, v0
	v_add_f32_e32 v4, -1.0, v1
	v_add_f32_e32 v8, 1.0, v1
	v_ldexp_f32 v0, v5, v0
	v_add_f32_e32 v5, 1.0, v4
	v_add_f32_e32 v19, -1.0, v8
	v_sub_f32_e32 v5, v1, v5
	v_sub_f32_e32 v1, v1, v19
	v_add_f32_e32 v5, v0, v5
	v_add_f32_e32 v0, v0, v1
	v_add_f32_e32 v19, v8, v0
	v_rcp_f32_e32 v21, v19
	v_sub_f32_e32 v1, v8, v19
	v_add_f32_e32 v8, v0, v1
	v_add_f32_e32 v1, v4, v5
	v_mul_f32_e32 v38, v1, v21
	v_sub_f32_e32 v0, v4, v1
	v_mul_f32_e32 v4, v19, v38
	v_fma_f32 v34, v38, v19, -v4
	v_fmac_f32_e32 v34, v38, v8
	v_add_f32_e32 v33, v5, v0
	v_add_f32_e32 v0, v4, v34
	v_sub_f32_e32 v5, v1, v0
	v_pk_add_f32 v[36:37], v[0:1], v[4:5] neg_lo:[0,1] neg_hi:[0,1]
	v_mov_b32_e32 v35, v0
	v_pk_add_f32 v[0:1], v[36:37], v[34:35] neg_lo:[0,1] neg_hi:[0,1]
	v_cmp_neq_f32_e32 vcc, s22, v2
	v_add_f32_e32 v1, v33, v1
	v_add_f32_e32 v0, v0, v1
	v_add_f32_e32 v1, v5, v0
	v_mul_f32_e32 v33, v21, v1
	v_mul_f32_e32 v4, v19, v33
	v_fma_f32 v34, v33, v19, -v4
	v_fmac_f32_e32 v34, v33, v8
	v_sub_f32_e32 v5, v5, v1
	v_add_f32_e32 v8, v0, v5
	v_add_f32_e32 v0, v4, v34
	v_sub_f32_e32 v5, v1, v0
	v_pk_add_f32 v[36:37], v[0:1], v[4:5] neg_lo:[0,1] neg_hi:[0,1]
	v_mov_b32_e32 v35, v0
	v_pk_add_f32 v[0:1], v[36:37], v[34:35] neg_lo:[0,1] neg_hi:[0,1]
	s_nop 0
	v_add_f32_e32 v1, v8, v1
	v_add_f32_e32 v0, v0, v1
	v_add_f32_e32 v1, v38, v33
	v_add_f32_e32 v0, v5, v0
	v_sub_f32_e32 v4, v1, v38
	v_mul_f32_e32 v0, v21, v0
	v_sub_f32_e32 v4, v33, v4
	v_add_f32_e32 v4, v4, v0
	v_add_f32_e32 v8, v1, v4
	v_mul_f32_e32 v21, v8, v8
	v_fmamk_f32 v0, v21, 0x3e9b6dac, v31
	v_fmaak_f32 v19, v21, v0, 0x3f2aaada
	v_cvt_f32_i32_e32 v0, v6
	v_sub_f32_e32 v1, v8, v1
	v_sub_f32_e32 v1, v4, v1
	v_ldexp_f32 v6, v1, 1
	v_mul_f32_e32 v1, v8, v21
	v_pk_mul_f32 v[34:35], v[0:1], v[18:19]
	v_ldexp_f32 v5, v8, 1
	v_fma_f32 v4, v0, s24, -v34
	v_fmac_f32_e32 v4, 0xb102e308, v0
	v_pk_add_f32 v[0:1], v[34:35], v[4:5]
	v_mov_b32_e32 v36, v34
	v_sub_f32_e32 v5, v1, v5
	v_sub_f32_e32 v5, v35, v5
	v_add_f32_e32 v37, v6, v5
	v_pk_add_f32 v[34:35], v[0:1], v[34:35] neg_lo:[0,1] neg_hi:[0,1]
	v_pk_add_f32 v[38:39], v[0:1], v[36:37]
	v_mov_b32_e32 v5, v0
	v_mov_b32_e32 v35, v39
	v_pk_add_f32 v[40:41], v[4:5], v[34:35] neg_lo:[0,1] neg_hi:[0,1]
	v_pk_add_f32 v[4:5], v[4:5], v[34:35]
	v_mov_b32_e32 v36, v37
	v_pk_add_f32 v[34:35], v[4:5], v[0:1] op_sel:[1,0] op_sel_hi:[0,1] neg_lo:[0,1] neg_hi:[0,1]
	v_pk_add_f32 v[42:43], v[38:39], v[34:35] op_sel_hi:[1,0] neg_lo:[0,1] neg_hi:[0,1]
	v_mov_b32_e32 v38, v39
	v_mov_b32_e32 v39, v5
	v_pk_mov_b32 v[34:35], v[0:1], v[34:35] op_sel:[1,0]
	v_mov_b32_e32 v37, v0
	v_pk_add_f32 v[34:35], v[38:39], v[34:35] neg_lo:[0,1] neg_hi:[0,1]
	v_mov_b32_e32 v42, v40
	v_pk_add_f32 v[0:1], v[36:37], v[34:35] neg_lo:[0,1] neg_hi:[0,1]
	v_mov_b32_e32 v41, v5
	v_pk_add_f32 v[34:35], v[42:43], v[0:1]
	s_nop 0
	v_pk_add_f32 v[36:37], v[34:35], v[34:35] op_sel:[0,1] op_sel_hi:[1,0]
	s_nop 0
	v_pk_add_f32 v[4:5], v[4:5], v[36:37] op_sel:[1,0] op_sel_hi:[0,1]
	v_mov_b32_e32 v35, v4
	v_pk_add_f32 v[38:39], v[34:35], v[40:41] neg_lo:[0,1] neg_hi:[0,1]
	v_mov_b32_e32 v1, v36
	v_sub_f32_e32 v5, v34, v38
	v_pk_add_f32 v[0:1], v[0:1], v[38:39] neg_lo:[0,1] neg_hi:[0,1]
	v_sub_f32_e32 v5, v40, v5
	v_add_f32_e32 v0, v0, v5
	v_add_f32_e32 v0, v0, v1
	v_add_f32_e32 v0, v4, v0
	v_cndmask_b32_e32 v0, v32, v0, vcc
	v_cmp_lt_f32_e64 vcc, |v2|, s25
	s_nop 1
	v_cndmask_b32_e32 v0, v0, v2, vcc
	v_xor_b32_e32 v1, 0x80000000, v0

.LBB0_578:
	s_or_b64 exec, exec, s[4:5]
	v_bitop3_b32 v0, v20, s30, 2 bitop3:0xc8
	v_lshlrev_b32_e32 v8, 2, v0
	v_lshl_add_u64 v[4:5], v[24:25], 0, v[8:9]
	flat_store_dword v[4:5], v1
	v_mov_b32_e32 v0, v253
	v_fmamk_f32 v0, v0, 0x3a000000, v29
	v_mul_f32_e32 v1, 0x4f800000, v0
	v_cmp_gt_f32_e32 vcc, s14, v0
	s_nop 1
	v_cndmask_b32_e32 v0, v0, v1, vcc
	v_sqrt_f32_e32 v1, v0
	s_nop 0
	v_add_u32_e32 v2, -1, v1
	v_add_u32_e32 v4, 1, v1
	v_fma_f32 v5, -v2, v1, v0
	v_fma_f32 v6, -v4, v1, v0
	v_cmp_ge_f32_e64 s[10:11], 0, v5
	s_nop 1
	v_cndmask_b32_e64 v1, v1, v2, s[10:11]
	v_cmp_lt_f32_e64 s[10:11], 0, v6
	s_nop 1
	v_cndmask_b32_e64 v1, v1, v4, s[10:11]
	v_mul_f32_e32 v2, 0x37800000, v1
	v_cndmask_b32_e32 v1, v1, v2, vcc
	v_cmp_class_f32_e32 vcc, v0, v30
	s_nop 1
	v_cndmask_b32_e32 v0, v1, v0, vcc
	v_div_scale_f32 v1, s[4:5], v0, v0, 1.0
	v_rcp_f32_e32 v2, v1
	v_div_scale_f32 v4, vcc, 1.0, v0, 1.0
	v_fma_f32 v5, -v1, v2, 1.0
	v_fmac_f32_e32 v2, v5, v2
	v_mul_f32_e32 v5, v4, v2
	v_fma_f32 v6, -v1, v5, v4
	v_fmac_f32_e32 v5, v6, v2
	v_fma_f32 v1, -v1, v5, v4
	v_div_fmas_f32 v1, v1, v2, v5
	v_div_fixup_f32 v0, v1, v0, 1.0
	v_add_f32_e32 v1, v3, v7
	v_fmac_f32_e32 v17, v1, v0
	v_cmp_ngt_f32_e32 vcc, 0, v17
	s_and_saveexec_b64 s[4:5], vcc
	s_xor_b64 s[4:5], exec, s[4:5]
	s_cbranch_execz .LBB0_580
	v_mul_f32_e32 v0, 0xbfb8aa3b, v17
	v_rndne_f32_e32 v1, v0
	v_sub_f32_e32 v2, v0, v1
	v_fma_f32 v0, v17, s15, -v0
	v_fmac_f32_e32 v0, 0xb2a5705f, v17
	v_add_f32_e32 v0, v2, v0
	v_cvt_i32_f32_e32 v1, v1
	v_exp_f32_e32 v0, v0
	v_cmp_nlt_f32_e32 vcc, s20, v17
	v_ldexp_f32 v0, v0, v1
	s_nop 0
	v_cndmask_b32_e32 v0, 0, v0, vcc
	v_cmp_ngt_f32_e32 vcc, s21, v17
	s_nop 1
	v_cndmask_b32_e32 v8, v32, v0, vcc
	v_add_f32_e32 v2, 1.0, v8
	v_add_f32_e32 v0, -1.0, v2
	v_sub_f32_e32 v1, v0, v2
	v_add_f32_e32 v1, 1.0, v1
	v_sub_f32_e32 v0, v8, v0
	v_add_f32_e32 v3, v0, v1
	v_frexp_mant_f32_e32 v4, v2
	v_cvt_f64_f32_e32 v[0:1], v2
	v_frexp_exp_i32_f64_e32 v0, v[0:1]
	v_cmp_gt_f32_e32 vcc, s23, v4
	s_nop 1
	v_subbrev_co_u32_e32 v17, vcc, 0, v0, vcc
	v_sub_u32_e32 v0, 0, v17
	v_ldexp_f32 v1, v2, v0
	v_add_f32_e32 v2, -1.0, v1
	v_add_f32_e32 v4, 1.0, v1
	v_ldexp_f32 v0, v3, v0
	v_add_f32_e32 v3, 1.0, v2
	v_add_f32_e32 v5, -1.0, v4
	v_sub_f32_e32 v3, v1, v3
	v_sub_f32_e32 v1, v1, v5
	v_add_f32_e32 v3, v0, v3
	v_add_f32_e32 v0, v0, v1
	v_add_f32_e32 v19, v4, v0
	v_rcp_f32_e32 v22, v19
	v_sub_f32_e32 v1, v4, v19
	v_add_f32_e32 v21, v0, v1
	v_add_f32_e32 v1, v2, v3
	v_mul_f32_e32 v33, v1, v22
	v_sub_f32_e32 v0, v2, v1
	v_mul_f32_e32 v2, v19, v33
	v_fma_f32 v4, v33, v19, -v2
	v_fmac_f32_e32 v4, v33, v21
	v_add_f32_e32 v23, v3, v0
	v_add_f32_e32 v0, v2, v4
	v_sub_f32_e32 v3, v1, v0
	v_pk_add_f32 v[6:7], v[0:1], v[2:3] neg_lo:[0,1] neg_hi:[0,1]
	v_mov_b32_e32 v5, v0
	v_pk_add_f32 v[0:1], v[6:7], v[4:5] neg_lo:[0,1] neg_hi:[0,1]
	v_cmp_neq_f32_e32 vcc, s22, v8
	v_add_f32_e32 v1, v23, v1
	v_add_f32_e32 v0, v0, v1
	v_add_f32_e32 v1, v3, v0
	v_mul_f32_e32 v23, v22, v1
	v_mul_f32_e32 v2, v19, v23
	v_fma_f32 v4, v23, v19, -v2
	v_fmac_f32_e32 v4, v23, v21
	v_sub_f32_e32 v3, v3, v1
	v_add_f32_e32 v19, v0, v3
	v_add_f32_e32 v0, v2, v4
	v_sub_f32_e32 v3, v1, v0
	v_pk_add_f32 v[6:7], v[0:1], v[2:3] neg_lo:[0,1] neg_hi:[0,1]
	v_mov_b32_e32 v5, v0
	v_pk_add_f32 v[0:1], v[6:7], v[4:5] neg_lo:[0,1] neg_hi:[0,1]
	s_nop 0
	v_add_f32_e32 v1, v19, v1
	v_add_f32_e32 v0, v0, v1
	v_add_f32_e32 v1, v33, v23
	v_add_f32_e32 v0, v3, v0
	v_sub_f32_e32 v2, v1, v33
	v_mul_f32_e32 v0, v22, v0
	v_sub_f32_e32 v2, v23, v2
	v_add_f32_e32 v2, v2, v0
	v_add_f32_e32 v4, v1, v2
	v_mul_f32_e32 v5, v4, v4
	v_fmamk_f32 v0, v5, 0x3e9b6dac, v31
	v_fmaak_f32 v19, v5, v0, 0x3f2aaada
	v_cvt_f32_i32_e32 v0, v17
	v_sub_f32_e32 v1, v4, v1
	v_sub_f32_e32 v1, v2, v1
	v_ldexp_f32 v6, v1, 1
	v_mul_f32_e32 v1, v4, v5
	v_ldexp_f32 v3, v4, 1
	v_pk_mul_f32 v[4:5], v[0:1], v[18:19]
	s_nop 0
	v_fma_f32 v2, v0, s24, -v4
	v_fmac_f32_e32 v2, 0xb102e308, v0
	v_pk_add_f32 v[0:1], v[4:5], v[2:3]
	s_nop 0
	v_sub_f32_e32 v3, v1, v3
	v_sub_f32_e32 v3, v5, v3
	v_add_f32_e32 v7, v6, v3
	v_mov_b32_e32 v6, v4
	v_pk_add_f32 v[4:5], v[0:1], v[4:5] neg_lo:[0,1] neg_hi:[0,1]
	v_pk_add_f32 v[22:23], v[0:1], v[6:7]
	v_mov_b32_e32 v3, v0
	v_mov_b32_e32 v5, v23
	v_pk_add_f32 v[34:35], v[2:3], v[4:5] neg_lo:[0,1] neg_hi:[0,1]
	v_pk_add_f32 v[2:3], v[2:3], v[4:5]
	v_mov_b32_e32 v6, v7
	v_pk_add_f32 v[4:5], v[2:3], v[0:1] op_sel:[1,0] op_sel_hi:[0,1] neg_lo:[0,1] neg_hi:[0,1]
	v_pk_add_f32 v[36:37], v[22:23], v[4:5] op_sel_hi:[1,0] neg_lo:[0,1] neg_hi:[0,1]
	v_mov_b32_e32 v22, v23
	v_mov_b32_e32 v23, v3
	v_pk_mov_b32 v[4:5], v[0:1], v[4:5] op_sel:[1,0]
	v_mov_b32_e32 v7, v0
	v_pk_add_f32 v[4:5], v[22:23], v[4:5] neg_lo:[0,1] neg_hi:[0,1]
	v_mov_b32_e32 v36, v34
	v_pk_add_f32 v[0:1], v[6:7], v[4:5] neg_lo:[0,1] neg_hi:[0,1]
	v_mov_b32_e32 v35, v3
	v_pk_add_f32 v[4:5], v[36:37], v[0:1]
	s_nop 0
	v_pk_add_f32 v[6:7], v[4:5], v[4:5] op_sel:[0,1] op_sel_hi:[1,0]
	s_nop 0
	v_pk_add_f32 v[2:3], v[2:3], v[6:7] op_sel:[1,0] op_sel_hi:[0,1]
	v_mov_b32_e32 v5, v2
	v_pk_add_f32 v[22:23], v[4:5], v[34:35] neg_lo:[0,1] neg_hi:[0,1]
	v_mov_b32_e32 v1, v6
	v_sub_f32_e32 v3, v4, v22
	v_pk_add_f32 v[0:1], v[0:1], v[22:23] neg_lo:[0,1] neg_hi:[0,1]
	v_sub_f32_e32 v3, v34, v3
	v_add_f32_e32 v0, v0, v3
	v_add_f32_e32 v0, v0, v1
	v_add_f32_e32 v0, v2, v0
	v_cndmask_b32_e32 v0, v32, v0, vcc
	v_cmp_lt_f32_e64 vcc, |v8|, s25
	s_nop 1
	v_cndmask_b32_e32 v0, v0, v8, vcc
	v_xor_b32_e32 v0, 0x80000000, v0

.LBB0_852:
	s_and_b64 s[14:15], s[70:71], exec
	s_cselect_b32 s24, 2, 4
	s_cmpk_lt_i32 s31, 0xf0
	s_cselect_b32 s25, 6, 5
	s_cselect_b32 s29, 8, 10
	s_lshl_b64 s[14:15], s[88:89], 8
	s_add_u32 s14, s59, s14
	s_addc_u32 s15, s18, s15
	s_add_i32 s0, s0, s5
	v_mbcnt_lo_u32_b32 v4, -1, 0
	v_mbcnt_hi_u32_b32 v4, -1, v4
	v_readlane_b32 s5, v254, 7
	v_and_or_b32 v130, v4, 31, s58
	v_ashrrev_i32_e32 v2, 2, v4
	v_lshlrev_b64 v[0:1], 8, v[130:131]
	v_and_b32_e32 v2, -8, v2
	v_add_u32_e32 v10, s5, v4
	s_max_i32 s0, s0, 0
	v_ashrrev_i32_e32 v3, 31, v2
	v_lshl_add_u64 v[0:1], s[14:15], 0, v[0:1]
	v_ashrrev_i32_e32 v11, 4, v10
	v_lshl_add_u64 v[0:1], v[2:3], 1, v[0:1]
	v_add_u32_e32 v2, s0, v11
	v_ashrrev_i32_e32 v3, 31, v2
	v_lshlrev_b32_e32 v12, 4, v4
	v_lshlrev_b64 v[2:3], 8, v[2:3]
	s_mov_b64 s[14:15], 0x2000
	flat_load_dwordx4 v[160:163], v[0:1]
	flat_load_dwordx4 v[156:159], v[0:1] offset:32
	flat_load_dwordx4 v[152:155], v[0:1] offset:64
	flat_load_dwordx4 v[148:151], v[0:1] offset:96
	flat_load_dwordx4 v[144:147], v[0:1] offset:128
	flat_load_dwordx4 v[136:139], v[0:1] offset:160
	v_and_b32_e32 v130, 0xf0, v12
	v_lshl_add_u64 v[4:5], v[2:3], 0, s[14:15]
	v_lshl_add_u64 v[6:7], s[46:47], 0, v[2:3]
	v_lshl_add_u64 v[6:7], v[6:7], 0, v[130:131]
	v_lshl_add_u64 v[8:9], s[46:47], 0, v[4:5]
	v_lshl_add_u64 v[8:9], v[8:9], 0, v[130:131]
	flat_load_dwordx4 v[120:123], v[6:7]
	flat_load_dwordx4 v[124:127], v[8:9]
	flat_load_dwordx4 v[140:143], v[0:1] offset:192
	flat_load_dwordx4 v[132:135], v[0:1] offset:224
	v_lshl_add_u64 v[0:1], s[76:77], 0, v[2:3]
	v_lshl_add_u64 v[0:1], v[0:1], 0, v[130:131]
	v_lshl_add_u64 v[2:3], s[76:77], 0, v[4:5]
	v_lshl_add_u64 v[2:3], v[2:3], 0, v[130:131]
	flat_load_dwordx4 v[112:115], v[0:1]
	flat_load_dwordx4 v[116:119], v[2:3]
	v_mov_b32_e32 v0, 0xf0
	v_sub_co_u32_e32 v0, vcc, s31, v0
	s_cmpk_gt_i32 s31, 0xbf
	v_readfirstlane_b32 s5, v0
	s_cselect_b64 s[16:17], -1, 0
	s_mul_i32 s14, s5, 6
	s_lshl_b32 s5, s5, 2
	s_add_i32 s15, s5, 0x60
	s_lshl_b32 s5, s31, 2
	s_addk_i32 s14, 0x120
	s_addk_i32 s1, 0xfa90
	s_add_i32 s36, s31, 0xffffff70
	s_add_i32 s37, s5, 0xfffffd00
	s_add_i32 s40, s31, 0x9e
	s_xor_b32 s84, s83, 0xf00
	s_add_u32 s5, s59, s52
	s_addc_u32 s41, s18, s53
	s_add_u32 s52, s5, s74
	s_addc_u32 s53, s41, s75
	s_add_u32 s5, s59, s78
	s_addc_u32 s41, s18, s79
	s_add_u32 s60, s5, s74
	s_addc_u32 s61, s41, s75
	s_lshl_b64 s[6:7], s[6:7], 24
	s_add_u32 s5, s19, s6
	s_addc_u32 s41, s28, s7
	s_lshl_b32 s6, s50, 7
	s_ashr_i32 s7, s6, 31
	s_lshl_b64 s[6:7], s[6:7], 1
	s_add_u32 s85, s5, s6
	s_addc_u32 s86, s41, s7
	s_ashr_i32 s5, s4, 31
	s_lshl_b64 s[4:5], s[4:5], 14
	s_add_u32 s78, s20, s4
	s_addc_u32 s79, s21, s5
	s_and_b64 s[4:5], vcc, exec
	s_cselect_b32 s6, 7, 6
	s_and_b64 s[4:5], s[70:71], exec
	s_cselect_b32 s7, s40, s37
	s_and_b64 s[4:5], vcc, exec
	s_cselect_b32 s15, s36, s15
	s_and_b64 s[4:5], s[70:71], exec
	s_cselect_b32 s36, 0, s37
	s_and_b64 s[4:5], vcc, exec
	v_and_b32_e32 v1, 0x70, v10
	s_movk_i32 s4, 0xf0
	s_waitcnt vmcnt(0)
	s_cselect_b32 s1, s1, s14
	s_cmpk_lt_i32 s31, 0xd0
	v_lshlrev_b32_e32 v0, 8, v11
	v_bitop3_b32 v1, v12, v1, s4 bitop3:0x6c
	s_mov_b32 s0, 0
	s_cselect_b32 s87, 3, s25
	s_cselect_b32 s64, s24, s29
	v_add3_u32 v0, 0, v0, v1
	s_cselect_b32 s65, s3, s6
	s_cselect_b32 s14, s7, s15
	s_cselect_b32 s15, s36, s1
	s_xor_b64 s[88:89], s[16:17], -1
	s_mov_b64 s[40:41], 0xb000
	s_waitcnt vmcnt(0) lgkmcnt(0)
	ds_write_b128 v0, v[120:123] offset:32768
	ds_write_b128 v0, v[124:127] offset:40960
	s_waitcnt lgkmcnt(0)
	s_barrier
	s_branch .LBB0_854

.LBB0_1086:
	s_cmpk_lt_i32 s31, 0xa0
	s_cbranch_scc0 .LBB0_838
	v_readlane_b32 s0, v254, 8
	v_readlane_b32 s1, v254, 9
	s_and_b64 vcc, exec, s[0:1]
	s_cbranch_vccnz .LBB0_1102
	v_mbcnt_lo_u32_b32 v0, -1, 0
	v_mbcnt_hi_u32_b32 v0, -1, v0
	s_nop 0
	v_cmp_eq_u32_e32 vcc, 0, v0
	s_and_saveexec_b64 s[4:5], vcc
	s_cbranch_execz .LBB0_1101
	v_mov_b64_e32 v[0:1], s[12:13]
	flat_load_dword v0, v[0:1] sc1
	s_waitcnt vmcnt(0) lgkmcnt(0)
	v_cmp_gt_u32_e32 vcc, 16, v0
	s_and_saveexec_b64 s[6:7], vcc
	s_cbranch_execz .LBB0_1100
	s_mov_b32 s0, 1
	s_mov_b64 s[46:47], 0
	s_branch .LBB0_1092

.LBB0_1102:
	s_add_i32 s0, s31, 0xa0
	s_and_b32 s0, s0, 0xff
	s_ashr_i32 s4, s0, 6
	s_bfe_u32 s1, s0, 0x20004
	s_ashr_i32 s5, s4, 31
	s_lshl_b32 s0, s1, 14
	s_lshl_b64 s[50:51], s[4:5], 12
	s_or_b32 s0, s0, 0x70000
	s_add_u32 s0, s50, s0
	v_readlane_b32 s3, v255, 28
	s_addc_u32 s7, s51, 0
	s_and_b32 s70, s3, 0xf00
	s_lshl_b32 s3, s4, 8
	s_or_b32 s6, s0, s70
	s_lshl_b32 s0, s1, 10
	s_ashr_i32 s14, s3, 31
	s_add_u32 s4, s0, s3
	s_addc_u32 s5, 0, s14
	s_lshl_b64 s[4:5], s[4:5], 8
	s_add_u32 s72, s82, s4
	s_addc_u32 s73, s26, s5
	s_bitset1_b32 s0, 12
	s_add_u32 s4, s0, s3
	s_addc_u32 s5, 0, s14
	s_lshl_b64 s[4:5], s[4:5], 8
	s_add_u32 s46, s82, s4
	s_addc_u32 s47, s26, s5
	s_lshl_b64 s[4:5], s[6:7], 8
	s_barrier
	s_add_u32 s4, s59, s4
	v_mbcnt_lo_u32_b32 v4, -1, 0
	v_mbcnt_hi_u32_b32 v4, -1, v4
	s_addc_u32 s5, s18, s5
	v_and_or_b32 v130, v4, 31, s58
	v_ashrrev_i32_e32 v2, 2, v4
	v_lshlrev_b64 v[0:1], 8, v[130:131]
	v_and_b32_e32 v2, -8, v2
	v_ashrrev_i32_e32 v3, 31, v2
	v_lshl_add_u64 v[0:1], s[4:5], 0, v[0:1]
	v_lshl_add_u64 v[0:1], v[2:3], 1, v[0:1]
	v_readlane_b32 s0, v254, 7
	flat_load_dwordx4 v[144:147], v[0:1]
	flat_load_dwordx4 v[140:143], v[0:1] offset:32
	flat_load_dwordx4 v[136:139], v[0:1] offset:64
	flat_load_dwordx4 v[132:135], v[0:1] offset:96
	flat_load_dwordx4 v[124:127], v[0:1] offset:128
	flat_load_dwordx4 v[120:123], v[0:1] offset:160
	flat_load_dwordx4 v[116:119], v[0:1] offset:192
	flat_load_dwordx4 v[112:115], v[0:1] offset:224
	v_add_u32_e32 v1, s0, v4
	v_ashrrev_i32_e32 v0, 4, v1
	v_lshlrev_b32_e32 v2, 4, v4
	v_and_b32_e32 v1, 0x70, v1
	s_movk_i32 s3, 0xf0
	v_bitop3_b32 v17, v2, v1, s3 bitop3:0x6c
	v_ashrrev_i32_e32 v1, 31, v0
	v_lshlrev_b64 v[8:9], 8, v[0:1]
	s_mov_b64 s[4:5], 0x2000
	v_lshlrev_b32_e32 v16, 8, v0
	v_and_b32_e32 v130, 0xf0, v2
	v_lshl_add_u64 v[0:1], s[46:47], 0, v[8:9]
	v_lshl_add_u64 v[12:13], v[8:9], 0, s[4:5]
	v_lshl_add_u64 v[8:9], s[72:73], 0, v[8:9]
	v_lshl_add_u64 v[4:5], s[46:47], 0, v[12:13]
	v_lshl_add_u64 v[8:9], v[8:9], 0, v[130:131]
	v_lshl_add_u64 v[12:13], s[72:73], 0, v[12:13]
	flat_load_dwordx4 v[8:11], v[8:9]
	v_lshl_add_u64 v[12:13], v[12:13], 0, v[130:131]
	v_lshl_add_u64 v[0:1], v[0:1], 0, v[130:131]
	v_lshl_add_u64 v[4:5], v[4:5], 0, v[130:131]
	flat_load_dwordx4 v[12:15], v[12:13]
	v_add3_u32 v16, 0, v16, v17
	flat_load_dwordx4 v[0:3], v[0:1]
	s_nop 0
	flat_load_dwordx4 v[4:7], v[4:5]
	s_waitcnt vmcnt(0)
	s_waitcnt vmcnt(0) lgkmcnt(0)
	ds_write_b128 v16, v[8:11] offset:32768
	ds_write_b128 v16, v[12:15] offset:40960
	s_waitcnt lgkmcnt(0)
	s_barrier
	v_mbcnt_lo_u32_b32 v165, -1, 0
	v_mbcnt_hi_u32_b32 v165, -1, v165
	s_nop 0
	v_add_u32_e32 v49, s0, v165
	s_movk_i32 s0, 0xff
	v_cmp_lt_i32_e32 vcc, s0, v49
	v_lshlrev_b32_e32 v48, 3, v165
	s_and_saveexec_b64 s[4:5], vcc
	s_xor_b64 s[4:5], exec, s[4:5]
	v_lshlrev_b32_e32 v48, 3, v165
	s_andn2_saveexec_b64 s[4:5], s[4:5]
	s_cbranch_execz .LBB0_1108
	v_readlane_b32 s0, v255, 27
	s_mov_b64 s[6:7], 0
	s_nop 0
	v_add_u32_e32 v8, s0, v165
	v_readlane_b32 s0, v254, 24
	s_nop 1
	v_add_u32_e32 v9, s0, v48
